# v28 + QUP epilogue second rope ladder: 29 of its 32 cos/sin loads issued up front under the ladder's lane mask (4 load round trips instead of 32)
# baseline (speedup 1.0000x reference)
.LBB0_953:
	s_or_b64 exec, exec, s[28:29]
	v_add_u32_e32 v135, 0x16200, v138
	v_cvt_pk_bf16_f32 v136, v136, s0
	v_or_b32_e32 v132, 32, v132
	global_store_short v135, v136, s[66:67]
	v_ashrrev_i32_e32 v135, 5, v132
	s_mov_b32 s20, 0x55555556
	v_mul_hi_i32 v136, v135, s20
	v_lshrrev_b32_e32 v138, 31, v136
	v_mul_f32_e32 v131, v16, v131
	v_add_u32_e32 v136, v136, v138
	s_nop 1
	v_mov_b32_dpp v16, v131 row_ror:8 row_mask:0xf bank_mask:0xf
	v_lshl_add_u32 v136, v136, 1, v136
	v_sub_u32_e32 v135, v135, v136
	v_cmp_eq_u32_e64 s[38:39], 2, v135
	s_and_b64 s[0:1], s[0:1], s[38:39]
	s_and_saveexec_b64 s[20:21], s[0:1]
	s_cbranch_execz .Lqrope_b_skip
	v_lshl_or_b32 v190, v133, 6, v50
	global_load_dwordx2 v[190:191], v190, s[76:77]
	v_lshl_or_b32 v192, v51, 6, v50
	global_load_dwordx2 v[192:193], v192, s[76:77]
	v_lshl_or_b32 v194, v52, 6, v50
	global_load_dwordx2 v[194:195], v194, s[76:77]
	v_lshl_or_b32 v196, v53, 6, v50
	global_load_dwordx2 v[196:197], v196, s[76:77]
	v_lshl_or_b32 v198, v54, 6, v50
	global_load_dwordx2 v[198:199], v198, s[76:77]
	v_lshl_or_b32 v200, v55, 6, v50
	global_load_dwordx2 v[200:201], v200, s[76:77]
	v_lshl_or_b32 v202, v56, 6, v50
	global_load_dwordx2 v[202:203], v202, s[76:77]
	v_lshl_or_b32 v204, v57, 6, v50
	global_load_dwordx2 v[204:205], v204, s[76:77]
	v_lshl_or_b32 v206, v58, 6, v50
	global_load_dwordx2 v[206:207], v206, s[76:77]
	v_lshl_or_b32 v208, v59, 6, v50
	global_load_dwordx2 v[208:209], v208, s[76:77]
	v_lshl_or_b32 v210, v60, 6, v50
	global_load_dwordx2 v[210:211], v210, s[76:77]
	v_lshl_or_b32 v212, v61, 6, v50
	global_load_dwordx2 v[212:213], v212, s[76:77]
	v_lshl_or_b32 v214, v62, 6, v50
	global_load_dwordx2 v[214:215], v214, s[76:77]
	v_lshl_or_b32 v216, v63, 6, v50
	global_load_dwordx2 v[216:217], v216, s[76:77]
	v_lshl_or_b32 v218, v64, 6, v50
	global_load_dwordx2 v[218:219], v218, s[76:77]
	v_lshl_or_b32 v220, v65, 6, v50
	global_load_dwordx2 v[220:221], v220, s[76:77]
	v_lshl_or_b32 v222, v34, 6, v50
	global_load_dwordx2 v[222:223], v222, s[76:77]
	v_lshl_or_b32 v224, v35, 6, v50
	global_load_dwordx2 v[224:225], v224, s[76:77]
	v_lshl_or_b32 v226, v36, 6, v50
	global_load_dwordx2 v[226:227], v226, s[76:77]
	v_lshl_or_b32 v228, v37, 6, v50
	global_load_dwordx2 v[228:229], v228, s[76:77]
	v_lshl_or_b32 v230, v38, 6, v50
	global_load_dwordx2 v[230:231], v230, s[76:77]
	v_lshl_or_b32 v236, v39, 6, v50
	global_load_dwordx2 v[236:237], v236, s[76:77]
	v_lshl_or_b32 v238, v40, 6, v50
	global_load_dwordx2 v[238:239], v238, s[76:77]
	v_lshl_or_b32 v240, v41, 6, v50
	global_load_dwordx2 v[240:241], v240, s[76:77]
	v_lshl_or_b32 v242, v42, 6, v50
	global_load_dwordx2 v[242:243], v242, s[76:77]
	v_lshl_or_b32 v244, v43, 6, v50
	global_load_dwordx2 v[244:245], v244, s[76:77]
	v_lshl_or_b32 v246, v44, 6, v50
	global_load_dwordx2 v[246:247], v246, s[76:77]
	v_lshl_or_b32 v248, v45, 6, v50
	global_load_dwordx2 v[248:249], v248, s[76:77]
	v_lshl_or_b32 v250, v46, 6, v50
	global_load_dwordx2 v[250:251], v250, s[76:77]
	s_waitcnt vmcnt(0)
.Lqrope_b_skip:
	s_or_b64 exec, exec, s[20:21]
	s_and_saveexec_b64 s[20:21], s[0:1]
	s_cbranch_execz .LBB0_955
	v_lshl_or_b32 v133, v133, 6, v50
	s_waitcnt lgkmcnt(1)
	s_waitcnt lgkmcnt(0)
	v_mov_b32_e32 v188, v190
	v_mov_b32_e32 v189, v191
	v_mul_f32_e32 v16, v189, v16
	v_cndmask_b32_e64 v16, v16, -v16, vcc
	v_fmac_f32_e32 v16, v131, v188
	v_mov_b32_e32 v131, v16
.LBB0_955:
	s_or_b64 exec, exec, s[20:21]
	v_mul_f32_e32 v17, v17, v137
	s_nop 1
	v_mov_b32_dpp v133, v17 row_ror:8 row_mask:0xf bank_mask:0xf
	s_waitcnt lgkmcnt(1)
	v_add_lshl_u32 v16, v130, v132, 1
	v_cvt_pk_bf16_f32 v130, v131, s0
	global_store_short v16, v130, s[66:67]
	s_and_saveexec_b64 s[20:21], s[0:1]
	s_cbranch_execz .LBB0_957
	v_lshl_or_b32 v51, v51, 6, v50
	s_waitcnt lgkmcnt(0)
	v_mov_b32_e32 v130, v192
	v_mov_b32_e32 v131, v193
	v_mul_f32_e32 v51, v131, v133
	v_cndmask_b32_e64 v51, v51, -v51, vcc
	v_fmac_f32_e32 v51, v17, v130
	v_mov_b32_e32 v17, v51
.LBB0_957:
	s_or_b64 exec, exec, s[20:21]
	v_mul_f32_e32 v18, v18, v139
	s_nop 1
	v_mov_b32_dpp v51, v18 row_ror:8 row_mask:0xf bank_mask:0xf
	v_add_u32_e32 v130, 0x600, v16
	v_cvt_pk_bf16_f32 v17, v17, s0
	global_store_short v130, v17, s[66:67]
	s_and_saveexec_b64 s[20:21], s[0:1]
	s_cbranch_execz .LBB0_959
	v_lshl_or_b32 v17, v52, 6, v50
	s_waitcnt lgkmcnt(0)
	v_mov_b32_e32 v130, v194
	v_mov_b32_e32 v131, v195
	v_mul_f32_e32 v17, v131, v51
	v_cndmask_b32_e64 v17, v17, -v17, vcc
	v_fmac_f32_e32 v17, v18, v130
	v_mov_b32_e32 v18, v17
.LBB0_959:
	s_or_b64 exec, exec, s[20:21]
	v_mul_f32_e32 v17, v19, v140
	s_nop 1
	v_mov_b32_dpp v19, v17 row_ror:8 row_mask:0xf bank_mask:0xf
	s_waitcnt lgkmcnt(1)
	v_add_u32_e32 v51, 0xc00, v16
	v_cvt_pk_bf16_f32 v18, v18, s0
	global_store_short v51, v18, s[66:67]
	s_and_saveexec_b64 s[20:21], s[0:1]
	s_cbranch_execz .LBB0_961
	v_lshl_or_b32 v18, v53, 6, v50
	s_waitcnt lgkmcnt(0)
	v_mov_b32_e32 v52, v196
	v_mov_b32_e32 v53, v197
	v_mul_f32_e32 v18, v53, v19
	v_cndmask_b32_e64 v18, v18, -v18, vcc
	v_fmac_f32_e32 v18, v17, v52
	v_mov_b32_e32 v17, v18
.LBB0_961:
	s_or_b64 exec, exec, s[20:21]
	v_mul_f32_e32 v18, v20, v141
	s_waitcnt lgkmcnt(0)
	s_nop 1
	v_mov_b32_dpp v19, v18 row_ror:8 row_mask:0xf bank_mask:0xf
	v_add_u32_e32 v20, 0x1200, v16
	v_cvt_pk_bf16_f32 v17, v17, s0
	global_store_short v20, v17, s[66:67]
	s_and_saveexec_b64 s[20:21], s[0:1]
	s_cbranch_execz .LBB0_963
	v_lshl_or_b32 v17, v54, 6, v50
	s_waitcnt lgkmcnt(0)
	v_mov_b32_e32 v52, v198
	v_mov_b32_e32 v53, v199
	v_mul_f32_e32 v17, v53, v19
	v_cndmask_b32_e64 v17, v17, -v17, vcc
	v_fmac_f32_e32 v17, v18, v52
	v_mov_b32_e32 v18, v17
.LBB0_963:
	s_or_b64 exec, exec, s[20:21]
	v_mul_f32_e32 v17, v21, v142
	s_waitcnt lgkmcnt(0)
	s_nop 1
	v_mov_b32_dpp v19, v17 row_ror:8 row_mask:0xf bank_mask:0xf
	v_add_u32_e32 v20, 0x3000, v16
	v_cvt_pk_bf16_f32 v18, v18, s0
	global_store_short v20, v18, s[66:67]
	s_and_saveexec_b64 s[20:21], s[0:1]
	s_cbranch_execz .LBB0_965
	v_lshl_or_b32 v18, v55, 6, v50
	s_waitcnt lgkmcnt(0)
	v_mov_b32_e32 v20, v200
	v_mov_b32_e32 v21, v201
	v_mul_f32_e32 v18, v21, v19
	v_cndmask_b32_e64 v18, v18, -v18, vcc
	v_fmac_f32_e32 v18, v17, v20
	v_mov_b32_e32 v17, v18
.LBB0_965:
	s_or_b64 exec, exec, s[20:21]
	v_mul_f32_e32 v18, v22, v143
	s_waitcnt lgkmcnt(0)
	s_nop 1
	v_mov_b32_dpp v19, v18 row_ror:8 row_mask:0xf bank_mask:0xf
	v_add_u32_e32 v20, 0x3600, v16
	v_cvt_pk_bf16_f32 v17, v17, s0
	global_store_short v20, v17, s[66:67]
	s_and_saveexec_b64 s[20:21], s[0:1]
	s_cbranch_execz .LBB0_967
	v_lshl_or_b32 v17, v56, 6, v50
	s_waitcnt lgkmcnt(0)
	v_mov_b32_e32 v20, v202
	v_mov_b32_e32 v21, v203
	v_mul_f32_e32 v17, v21, v19
	v_cndmask_b32_e64 v17, v17, -v17, vcc
	v_fmac_f32_e32 v17, v18, v20
	v_mov_b32_e32 v18, v17
.LBB0_967:
	s_or_b64 exec, exec, s[20:21]
	v_mul_f32_e32 v17, v23, v144
	s_waitcnt lgkmcnt(0)
	s_nop 1
	v_mov_b32_dpp v19, v17 row_ror:8 row_mask:0xf bank_mask:0xf
	v_add_u32_e32 v20, 0x3c00, v16
	v_cvt_pk_bf16_f32 v18, v18, s0
	global_store_short v20, v18, s[66:67]
	s_and_saveexec_b64 s[20:21], s[0:1]
	s_cbranch_execz .LBB0_969
	v_lshl_or_b32 v18, v57, 6, v50
	s_waitcnt lgkmcnt(0)
	v_mov_b32_e32 v20, v204
	v_mov_b32_e32 v21, v205
	v_mul_f32_e32 v18, v21, v19
	v_cndmask_b32_e64 v18, v18, -v18, vcc
	v_fmac_f32_e32 v18, v17, v20
	v_mov_b32_e32 v17, v18
.LBB0_969:
	s_or_b64 exec, exec, s[20:21]
	v_mul_f32_e32 v18, v24, v145
	s_waitcnt lgkmcnt(0)
	s_nop 1
	v_mov_b32_dpp v19, v18 row_ror:8 row_mask:0xf bank_mask:0xf
	v_add_u32_e32 v20, 0x4200, v16
	v_cvt_pk_bf16_f32 v17, v17, s0
	global_store_short v20, v17, s[66:67]
	s_and_saveexec_b64 s[20:21], s[0:1]
	s_cbranch_execz .LBB0_971
	v_lshl_or_b32 v17, v58, 6, v50
	s_waitcnt lgkmcnt(0)
	v_mov_b32_e32 v20, v206
	v_mov_b32_e32 v21, v207
	v_mul_f32_e32 v17, v21, v19
	v_cndmask_b32_e64 v17, v17, -v17, vcc
	v_fmac_f32_e32 v17, v18, v20
	v_mov_b32_e32 v18, v17
.LBB0_971:
	s_or_b64 exec, exec, s[20:21]
	v_mul_f32_e32 v17, v25, v146
	s_waitcnt lgkmcnt(0)
	s_nop 1
	v_mov_b32_dpp v19, v17 row_ror:8 row_mask:0xf bank_mask:0xf
	v_add_u32_e32 v20, 0x6000, v16
	v_cvt_pk_bf16_f32 v18, v18, s0
	global_store_short v20, v18, s[66:67]
	s_and_saveexec_b64 s[20:21], s[0:1]
	s_cbranch_execz .LBB0_973
	v_lshl_or_b32 v18, v59, 6, v50
	s_waitcnt lgkmcnt(0)
	v_mov_b32_e32 v20, v208
	v_mov_b32_e32 v21, v209
	v_mul_f32_e32 v18, v21, v19
	v_cndmask_b32_e64 v18, v18, -v18, vcc
	v_fmac_f32_e32 v18, v17, v20
	v_mov_b32_e32 v17, v18
.LBB0_973:
	s_or_b64 exec, exec, s[20:21]
	v_mul_f32_e32 v18, v26, v147
	s_waitcnt lgkmcnt(0)
	s_nop 1
	v_mov_b32_dpp v19, v18 row_ror:8 row_mask:0xf bank_mask:0xf
	v_add_u32_e32 v20, 0x6600, v16
	v_cvt_pk_bf16_f32 v17, v17, s0
	global_store_short v20, v17, s[66:67]
	s_and_saveexec_b64 s[20:21], s[0:1]
	s_cbranch_execz .LBB0_975
	v_lshl_or_b32 v17, v60, 6, v50
	s_waitcnt lgkmcnt(0)
	v_mov_b32_e32 v20, v210
	v_mov_b32_e32 v21, v211
	v_mul_f32_e32 v17, v21, v19
	v_cndmask_b32_e64 v17, v17, -v17, vcc
	v_fmac_f32_e32 v17, v18, v20
	v_mov_b32_e32 v18, v17
.LBB0_975:
	s_or_b64 exec, exec, s[20:21]
	v_mul_f32_e32 v17, v27, v148
	s_waitcnt lgkmcnt(0)
	s_nop 1
	v_mov_b32_dpp v19, v17 row_ror:8 row_mask:0xf bank_mask:0xf
	v_add_u32_e32 v20, 0x6c00, v16
	v_cvt_pk_bf16_f32 v18, v18, s0
	global_store_short v20, v18, s[66:67]
	s_and_saveexec_b64 s[20:21], s[0:1]
	s_cbranch_execz .LBB0_977
	v_lshl_or_b32 v18, v61, 6, v50
	s_waitcnt lgkmcnt(0)
	v_mov_b32_e32 v20, v212
	v_mov_b32_e32 v21, v213
	v_mul_f32_e32 v18, v21, v19
	v_cndmask_b32_e64 v18, v18, -v18, vcc
	v_fmac_f32_e32 v18, v17, v20
	v_mov_b32_e32 v17, v18
.LBB0_977:
	s_or_b64 exec, exec, s[20:21]
	v_mul_f32_e32 v18, v28, v149
	s_waitcnt lgkmcnt(0)
	s_nop 1
	v_mov_b32_dpp v19, v18 row_ror:8 row_mask:0xf bank_mask:0xf
	v_add_u32_e32 v20, 0x7200, v16
	v_cvt_pk_bf16_f32 v17, v17, s0
	global_store_short v20, v17, s[66:67]
	s_and_saveexec_b64 s[20:21], s[0:1]
	s_cbranch_execz .LBB0_979
	v_lshl_or_b32 v17, v62, 6, v50
	s_waitcnt lgkmcnt(0)
	v_mov_b32_e32 v20, v214
	v_mov_b32_e32 v21, v215
	v_mul_f32_e32 v17, v21, v19
	v_cndmask_b32_e64 v17, v17, -v17, vcc
	v_fmac_f32_e32 v17, v18, v20
	v_mov_b32_e32 v18, v17
.LBB0_979:
	s_or_b64 exec, exec, s[20:21]
	v_mul_f32_e32 v17, v29, v150
	s_waitcnt lgkmcnt(0)
	s_nop 1
	v_mov_b32_dpp v19, v17 row_ror:8 row_mask:0xf bank_mask:0xf
	v_add_u32_e32 v20, 0x9000, v16
	v_cvt_pk_bf16_f32 v18, v18, s0
	global_store_short v20, v18, s[66:67]
	s_and_saveexec_b64 s[20:21], s[0:1]
	s_cbranch_execz .LBB0_981
	v_lshl_or_b32 v18, v63, 6, v50
	s_waitcnt lgkmcnt(0)
	v_mov_b32_e32 v20, v216
	v_mov_b32_e32 v21, v217
	v_mul_f32_e32 v18, v21, v19
	v_cndmask_b32_e64 v18, v18, -v18, vcc
	v_fmac_f32_e32 v18, v17, v20
	v_mov_b32_e32 v17, v18
.LBB0_981:
	s_or_b64 exec, exec, s[20:21]
	v_mul_f32_e32 v18, v30, v151
	s_waitcnt lgkmcnt(0)
	s_nop 1
	v_mov_b32_dpp v19, v18 row_ror:8 row_mask:0xf bank_mask:0xf
	v_add_u32_e32 v20, 0x9600, v16
	v_cvt_pk_bf16_f32 v17, v17, s0
	global_store_short v20, v17, s[66:67]
	s_and_saveexec_b64 s[20:21], s[0:1]
	s_cbranch_execz .LBB0_983
	v_lshl_or_b32 v17, v64, 6, v50
	s_waitcnt lgkmcnt(0)
	v_mov_b32_e32 v20, v218
	v_mov_b32_e32 v21, v219
	v_mul_f32_e32 v17, v21, v19
	v_cndmask_b32_e64 v17, v17, -v17, vcc
	v_fmac_f32_e32 v17, v18, v20
	v_mov_b32_e32 v18, v17
.LBB0_983:
	s_or_b64 exec, exec, s[20:21]
	v_mul_f32_e32 v17, v31, v152
	s_waitcnt lgkmcnt(0)
	s_nop 1
	v_mov_b32_dpp v19, v17 row_ror:8 row_mask:0xf bank_mask:0xf
	v_add_u32_e32 v20, 0x9c00, v16
	v_cvt_pk_bf16_f32 v18, v18, s0
	global_store_short v20, v18, s[66:67]
	s_and_saveexec_b64 s[20:21], s[0:1]
	s_cbranch_execz .LBB0_985
	v_lshl_or_b32 v18, v65, 6, v50
	s_waitcnt lgkmcnt(0)
	v_mov_b32_e32 v20, v220
	v_mov_b32_e32 v21, v221
	v_mul_f32_e32 v18, v21, v19
	v_cndmask_b32_e64 v18, v18, -v18, vcc
	v_fmac_f32_e32 v18, v17, v20
	v_mov_b32_e32 v17, v18
.LBB0_985:
	s_or_b64 exec, exec, s[20:21]
	v_mul_f32_e32 v0, v0, v153
	s_nop 1
	v_mov_b32_dpp v18, v0 row_ror:8 row_mask:0xf bank_mask:0xf
	s_waitcnt lgkmcnt(1)
	v_add_u32_e32 v19, 0xa200, v16
	v_cvt_pk_bf16_f32 v17, v17, s0
	global_store_short v19, v17, s[66:67]
	s_and_saveexec_b64 s[20:21], s[0:1]
	s_cbranch_execz .LBB0_987
	v_lshl_or_b32 v17, v34, 6, v50
	s_waitcnt lgkmcnt(0)
	v_mov_b32_e32 v20, v222
	v_mov_b32_e32 v21, v223
	v_mul_f32_e32 v17, v21, v18
	v_cndmask_b32_e64 v17, v17, -v17, vcc
	v_fmac_f32_e32 v17, v0, v20
	v_mov_b32_e32 v0, v17
.LBB0_987:
	s_or_b64 exec, exec, s[20:21]
	v_mul_f32_e32 v1, v1, v154
	s_nop 1
	v_mov_b32_dpp v17, v1 row_ror:8 row_mask:0xf bank_mask:0xf
	s_waitcnt lgkmcnt(1)
	v_add_u32_e32 v18, 0xc000, v16
	v_cvt_pk_bf16_f32 v0, v0, s0
	global_store_short v18, v0, s[66:67]
	s_and_saveexec_b64 s[20:21], s[0:1]
	s_cbranch_execz .LBB0_989
	v_lshl_or_b32 v0, v35, 6, v50
	s_waitcnt lgkmcnt(0)
	v_mov_b32_e32 v18, v224
	v_mov_b32_e32 v19, v225
	v_mul_f32_e32 v0, v19, v17
	v_cndmask_b32_e64 v0, v0, -v0, vcc
	v_fmac_f32_e32 v0, v1, v18
	v_mov_b32_e32 v1, v0
.LBB0_989:
	s_or_b64 exec, exec, s[20:21]
	v_mul_f32_e32 v0, v2, v155
	s_nop 1
	v_mov_b32_dpp v2, v0 row_ror:8 row_mask:0xf bank_mask:0xf
	s_waitcnt lgkmcnt(1)
	v_add_u32_e32 v17, 0xc600, v16
	v_cvt_pk_bf16_f32 v1, v1, s0
	global_store_short v17, v1, s[66:67]
	s_and_saveexec_b64 s[20:21], s[0:1]
	s_cbranch_execz .LBB0_991
	v_lshl_or_b32 v1, v36, 6, v50
	s_waitcnt lgkmcnt(0)
	v_mov_b32_e32 v18, v226
	v_mov_b32_e32 v19, v227
	v_mul_f32_e32 v1, v19, v2
	v_cndmask_b32_e64 v1, v1, -v1, vcc
	v_fmac_f32_e32 v1, v0, v18
	v_mov_b32_e32 v0, v1
.LBB0_991:
	s_or_b64 exec, exec, s[20:21]
	v_mul_f32_e32 v1, v3, v156
	s_waitcnt lgkmcnt(0)
	s_nop 1
	v_mov_b32_dpp v2, v1 row_ror:8 row_mask:0xf bank_mask:0xf
	v_add_u32_e32 v3, 0xcc00, v16
	v_cvt_pk_bf16_f32 v0, v0, s0
	global_store_short v3, v0, s[66:67]
	s_and_saveexec_b64 s[20:21], s[0:1]
	s_cbranch_execz .LBB0_993
	v_lshl_or_b32 v0, v37, 6, v50
	s_waitcnt lgkmcnt(0)
	v_mov_b32_e32 v18, v228
	v_mov_b32_e32 v19, v229
	v_mul_f32_e32 v0, v19, v2
	v_cndmask_b32_e64 v0, v0, -v0, vcc
	v_fmac_f32_e32 v0, v1, v18
	v_mov_b32_e32 v1, v0
.LBB0_993:
	s_or_b64 exec, exec, s[20:21]
	v_mul_f32_e32 v0, v4, v157
	s_waitcnt lgkmcnt(0)
	s_nop 1
	v_mov_b32_dpp v2, v0 row_ror:8 row_mask:0xf bank_mask:0xf
	v_add_u32_e32 v3, 0xd200, v16
	v_cvt_pk_bf16_f32 v1, v1, s0
	global_store_short v3, v1, s[66:67]
	s_and_saveexec_b64 s[20:21], s[0:1]
	s_cbranch_execz .LBB0_995
	v_lshl_or_b32 v1, v38, 6, v50
	s_waitcnt lgkmcnt(0)
	v_mov_b32_e32 v18, v230
	v_mov_b32_e32 v19, v231
	v_mul_f32_e32 v1, v19, v2
	v_cndmask_b32_e64 v1, v1, -v1, vcc
	v_fmac_f32_e32 v1, v0, v18
	v_mov_b32_e32 v0, v1
.LBB0_995:
	s_or_b64 exec, exec, s[20:21]
	v_mul_f32_e32 v1, v5, v160
	s_waitcnt lgkmcnt(0)
	s_nop 1
	v_mov_b32_dpp v2, v1 row_ror:8 row_mask:0xf bank_mask:0xf
	v_add_u32_e32 v3, 0xf000, v16
	v_cvt_pk_bf16_f32 v0, v0, s0
	global_store_short v3, v0, s[66:67]
	s_and_saveexec_b64 s[20:21], s[0:1]
	s_cbranch_execz .LBB0_997
	v_lshl_or_b32 v0, v39, 6, v50
	s_waitcnt lgkmcnt(0)
	v_mov_b32_e32 v4, v236
	v_mov_b32_e32 v5, v237
	v_mul_f32_e32 v0, v5, v2
	v_cndmask_b32_e64 v0, v0, -v0, vcc
	v_fmac_f32_e32 v0, v1, v4
	v_mov_b32_e32 v1, v0
.LBB0_997:
	s_or_b64 exec, exec, s[20:21]
	v_mul_f32_e32 v0, v6, v161
	s_waitcnt lgkmcnt(0)
	s_nop 1
	v_mov_b32_dpp v2, v0 row_ror:8 row_mask:0xf bank_mask:0xf
	v_add_u32_e32 v3, 0xf600, v16
	v_cvt_pk_bf16_f32 v1, v1, s0
	global_store_short v3, v1, s[66:67]
	s_and_saveexec_b64 s[20:21], s[0:1]
	s_cbranch_execz .LBB0_999
	v_lshl_or_b32 v1, v40, 6, v50
	s_waitcnt lgkmcnt(0)
	v_mov_b32_e32 v4, v238
	v_mov_b32_e32 v5, v239
	v_mul_f32_e32 v1, v5, v2
	v_cndmask_b32_e64 v1, v1, -v1, vcc
	v_fmac_f32_e32 v1, v0, v4
	v_mov_b32_e32 v0, v1
.LBB0_999:
	s_or_b64 exec, exec, s[20:21]
	v_mul_f32_e32 v1, v7, v180
	s_waitcnt lgkmcnt(0)
	s_nop 1
	v_mov_b32_dpp v2, v1 row_ror:8 row_mask:0xf bank_mask:0xf
	v_add_u32_e32 v3, 0xfc00, v16
	v_cvt_pk_bf16_f32 v0, v0, s0
	global_store_short v3, v0, s[66:67]
	s_and_saveexec_b64 s[20:21], s[0:1]
	s_cbranch_execz .LBB0_1001
	v_lshl_or_b32 v0, v41, 6, v50
	s_waitcnt lgkmcnt(0)
	v_mov_b32_e32 v4, v240
	v_mov_b32_e32 v5, v241
	v_mul_f32_e32 v0, v5, v2
	v_cndmask_b32_e64 v0, v0, -v0, vcc
	v_fmac_f32_e32 v0, v1, v4
	v_mov_b32_e32 v1, v0
.LBB0_1001:
	s_or_b64 exec, exec, s[20:21]
	v_mul_f32_e32 v0, v8, v181
	s_waitcnt lgkmcnt(0)
	s_nop 1
	v_mov_b32_dpp v2, v0 row_ror:8 row_mask:0xf bank_mask:0xf
	v_add_u32_e32 v3, 0x10200, v16
	v_cvt_pk_bf16_f32 v1, v1, s0
	global_store_short v3, v1, s[66:67]
	s_and_saveexec_b64 s[20:21], s[0:1]
	s_cbranch_execz .LBB0_1003
	v_lshl_or_b32 v1, v42, 6, v50
	s_waitcnt lgkmcnt(0)
	v_mov_b32_e32 v4, v242
	v_mov_b32_e32 v5, v243
	v_mul_f32_e32 v1, v5, v2
	v_cndmask_b32_e64 v1, v1, -v1, vcc
	v_fmac_f32_e32 v1, v0, v4
	v_mov_b32_e32 v0, v1
.LBB0_1003:
	s_or_b64 exec, exec, s[20:21]
	v_mul_f32_e32 v1, v9, v182
	s_waitcnt lgkmcnt(0)
	s_nop 1
	v_mov_b32_dpp v2, v1 row_ror:8 row_mask:0xf bank_mask:0xf
	v_add_u32_e32 v3, 0x12000, v16
	v_cvt_pk_bf16_f32 v0, v0, s0
	global_store_short v3, v0, s[66:67]
	s_and_saveexec_b64 s[20:21], s[0:1]
	s_cbranch_execz .LBB0_1005
	v_lshl_or_b32 v0, v43, 6, v50
	s_waitcnt lgkmcnt(0)
	v_mov_b32_e32 v4, v244
	v_mov_b32_e32 v5, v245
	v_mul_f32_e32 v0, v5, v2
	v_cndmask_b32_e64 v0, v0, -v0, vcc
	v_fmac_f32_e32 v0, v1, v4
	v_mov_b32_e32 v1, v0
.LBB0_1005:
	s_or_b64 exec, exec, s[20:21]
	v_mul_f32_e32 v0, v10, v183
	s_waitcnt lgkmcnt(0)
	s_nop 1
	v_mov_b32_dpp v2, v0 row_ror:8 row_mask:0xf bank_mask:0xf
	v_add_u32_e32 v3, 0x12600, v16
	v_cvt_pk_bf16_f32 v1, v1, s0
	global_store_short v3, v1, s[66:67]
	s_and_saveexec_b64 s[20:21], s[0:1]
	s_cbranch_execz .LBB0_1007
	v_lshl_or_b32 v1, v44, 6, v50
	s_waitcnt lgkmcnt(0)
	v_mov_b32_e32 v4, v246
	v_mov_b32_e32 v5, v247
	v_mul_f32_e32 v1, v5, v2
	v_cndmask_b32_e64 v1, v1, -v1, vcc
	v_fmac_f32_e32 v1, v0, v4
	v_mov_b32_e32 v0, v1
.LBB0_1007:
	s_or_b64 exec, exec, s[20:21]
	v_mul_f32_e32 v1, v11, v184
	s_waitcnt lgkmcnt(0)
	s_nop 1
	v_mov_b32_dpp v2, v1 row_ror:8 row_mask:0xf bank_mask:0xf
	v_add_u32_e32 v3, 0x12c00, v16
	v_cvt_pk_bf16_f32 v0, v0, s0
	global_store_short v3, v0, s[66:67]
	s_and_saveexec_b64 s[20:21], s[0:1]
	s_cbranch_execz .LBB0_1009
	v_lshl_or_b32 v0, v45, 6, v50
	s_waitcnt lgkmcnt(0)
	v_mov_b32_e32 v4, v248
	v_mov_b32_e32 v5, v249
	v_mul_f32_e32 v0, v5, v2
	v_cndmask_b32_e64 v0, v0, -v0, vcc
	v_fmac_f32_e32 v0, v1, v4
	v_mov_b32_e32 v1, v0
.LBB0_1009:
	s_or_b64 exec, exec, s[20:21]
	v_mul_f32_e32 v0, v12, v185
	s_waitcnt lgkmcnt(0)
	s_nop 1
	v_mov_b32_dpp v2, v0 row_ror:8 row_mask:0xf bank_mask:0xf
	v_add_u32_e32 v3, 0x13200, v16
	v_cvt_pk_bf16_f32 v1, v1, s0
	global_store_short v3, v1, s[66:67]
	s_and_saveexec_b64 s[20:21], s[0:1]
	s_cbranch_execz .LBB0_1011
	v_lshl_or_b32 v1, v46, 6, v50
	s_waitcnt lgkmcnt(0)
	v_mov_b32_e32 v4, v250
	v_mov_b32_e32 v5, v251
	v_mul_f32_e32 v1, v5, v2
	v_cndmask_b32_e64 v1, v1, -v1, vcc
	v_fmac_f32_e32 v1, v0, v4
	v_mov_b32_e32 v0, v1
